# expert_red: all 19 loads of a token (16 per-XCD partial sums, gates, row sums) issued in one burst instead of dependent dribbles
# speedup vs baseline: 1.1714x; 1.0033x over previous
; __device__ void ph_expert_red(const P& p) {
;     ...
;   for (int it = blockIdx.x; it < TT / 4; it += gridDim.x) {
;     const size_t t = (size_t)it * 4 + wid;
; #pragma unroll
;     for (int hf = 0; hf < 2; ++hf) {
;       float a = 0.f;
; #pragma unroll
;       for (int x = 0; x < 8; ++x) a += partial[((size_t)x * TT + t) * 128 + hf * 64 + lane];
;       a *= (1.f / SU) * rsqrtf(p_ssq2[t] * (1.f / 1024.f) + EPS);
;       float act = 0.5f * a * (1.f + erff(a * 0.70710678118654752f));
;       gates[t * 128 + hf * 64 + lane] *= act;
;     }
.LBB0_980:
	s_or_b64 exec, exec, s[4:5]
	v_mov_b32_e32 v9, v49
	v_bfi_b32 v7, s16, v8, v7
	v_mul_f32_e32 v6, 0.5, v6
	v_readlane_b32 s4, v228, 10
	v_add_f32_e32 v7, 1.0, v7
	s_add_i32 s2, s2, s4
	v_mul_f32_e32 v6, v6, v7
	s_cmpk_lt_i32 s2, 0x2100
	v_readlane_b32 s5, v228, 11
	s_nop 0
	v_mul_f32_e32 v6, v9, v6
	global_store_dword v[10:11], v6, off offset:256
	s_cbranch_scc0 .LBB0_989
.LBB0_981:
	s_ashr_i32 s3, s2, 31
	v_lshl_add_u64 v[6:7], s[2:3], 2, v[0:1]
	v_lshlrev_b64 v[10:11], 9, v[6:7]
	v_lshl_add_u64 v[8:9], v[6:7], 2, s[0:1]
	v_lshl_add_u64 v[6:7], v[2:3], 0, v[10:11]
	v_add_co_u32_e32 v16, vcc, 0x1080000, v6
	s_nop 1
	v_addc_co_u32_e32 v17, vcc, 0, v7, vcc
	v_add_co_u32_e32 v18, vcc, 0x2100000, v6
	s_nop 1
	v_addc_co_u32_e32 v19, vcc, 0, v7, vcc
	v_add_co_u32_e32 v20, vcc, 0x3180000, v6
	s_nop 1
	v_addc_co_u32_e32 v21, vcc, 0, v7, vcc
	v_add_co_u32_e32 v22, vcc, 0x4200000, v6
	s_nop 1
	v_addc_co_u32_e32 v23, vcc, 0, v7, vcc
	v_add_co_u32_e32 v24, vcc, 0x5280000, v6
	s_nop 1
	v_addc_co_u32_e32 v25, vcc, 0, v7, vcc
	v_add_co_u32_e32 v26, vcc, 0x6300000, v6
	s_nop 1
	v_addc_co_u32_e32 v27, vcc, 0, v7, vcc
	global_load_dword v28, v[6:7], off
	global_load_dword v29, v[16:17], off
	global_load_dword v30, v[18:19], off
	global_load_dword v31, v[20:21], off
	global_load_dword v32, v[22:23], off
	global_load_dword v33, v[24:25], off
	global_load_dword v34, v[26:27], off
	global_load_dword v35, v[8:9], off
	v_lshl_add_u64 v[38:39], v[4:5], 0, v[10:11]
	v_mov_b32_e32 v36, 0x7380000
	v_mov_b32_e32 v37, 0
	v_lshl_add_u64 v[36:37], v[6:7], 0, v[36:37]
	global_load_dword v40, v[6:7], off offset:256
	global_load_dword v41, v[16:17], off offset:256
	global_load_dword v42, v[18:19], off offset:256
	global_load_dword v43, v[20:21], off offset:256
	global_load_dword v44, v[22:23], off offset:256
	global_load_dword v45, v[24:25], off offset:256
	global_load_dword v46, v[26:27], off offset:256
	global_load_dword v47, v[36:37], off offset:256
	global_load_dword v48, v[38:39], off
	global_load_dword v49, v[38:39], off offset:256
	global_load_dword v50, v[8:9], off
	v_add_co_u32_e32 v16, vcc, 0x7380000, v6
	s_waitcnt vmcnt(0)
	v_fmamk_f32 v18, v35, 0x3a800000, v12
	v_addc_co_u32_e32 v17, vcc, 0, v7, vcc
	global_load_dword v16, v[16:17], off
	v_add_f32_e32 v17, 0, v28
	v_add_f32_e32 v17, v17, v29
	v_mul_f32_e32 v19, 0x4b800000, v18
	v_cmp_gt_f32_e32 vcc, s6, v18
	v_add_f32_e32 v17, v17, v30
	v_add_f32_e32 v17, v17, v31
	v_cndmask_b32_e32 v18, v18, v19, vcc
	v_rsq_f32_e32 v18, v18
	v_add_f32_e32 v17, v17, v32
	v_add_f32_e32 v17, v17, v33
	v_add_f32_e32 v17, v17, v34
	s_waitcnt vmcnt(0)
	v_add_f32_e32 v16, v17, v16
	v_mul_f32_e32 v17, 0x45800000, v18
	v_cndmask_b32_e32 v17, v18, v17, vcc
	v_mul_f32_e32 v17, 0x3c800000, v17
	v_mul_f32_e32 v16, v16, v17
	v_mul_f32_e32 v17, 0x3f3504f3, v16
	v_cmp_nlt_f32_e64 s[4:5], |v17|, 1.0
	s_and_saveexec_b64 s[18:19], s[4:5]
	s_xor_b64 s[4:5], exec, s[18:19]
	s_cbranch_execz .LBB0_983
	v_fma_f32 v18, |v17|, s7, v14
	v_fma_f32 v18, |v17|, v18, s8
	v_fma_f32 v18, |v17|, v18, s9
	v_fma_f32 v18, |v17|, v18, s10
	v_fma_f32 v18, |v17|, v18, s11
	v_fma_f32 v18, |v17|, v18, s12
	v_fma_f32 v18, |v17|, v18, |v17|
	v_mul_f32_e32 v19, 0xbfb8aa3b, v18
	v_fma_f32 v20, v18, s13, -v19
	v_rndne_f32_e32 v21, v19
	v_fmac_f32_e32 v20, 0xb2a5705f, v18
	v_sub_f32_e32 v19, v19, v21
	v_add_f32_e32 v19, v19, v20
	v_cvt_i32_f32_e32 v20, v21
	v_exp_f32_e32 v19, v19
	v_cmp_nlt_f32_e32 vcc, s14, v18
	v_ldexp_f32 v19, v19, v20
	s_nop 0
	v_cndmask_b32_e32 v19, 0, v19, vcc
	v_cmp_ngt_f32_e32 vcc, s15, v18
	s_nop 1
	v_cndmask_b32_e32 v18, v15, v19, vcc
	v_sub_f32_e32 v18, 1.0, v18
.LBB0_983:
	s_andn2_saveexec_b64 s[4:5], s[4:5]
	v_mul_f32_e32 v18, v17, v17
	v_fmamk_f32 v19, v18, 0xba1345e1, v13
	v_fmaak_f32 v19, v18, v19, 0xbcdac9b8
	v_fmaak_f32 v19, v18, v19, 0x3de703be
	v_fmaak_f32 v19, v18, v19, 0xbec09330
	v_fmaak_f32 v18, v18, v19, 0x3e0375d0
	v_fma_f32 v18, |v17|, v18, |v17|
	s_or_b64 exec, exec, s[4:5]
	v_lshl_add_u64 v[10:11], v[4:5], 0, v[10:11]
	v_mov_b32_e32 v28, v48
	v_mul_f32_e32 v19, 0.5, v16
	v_bfi_b32 v17, s16, v18, v17
	v_add_co_u32_e32 v16, vcc, 0x1080000, v6
	v_add_f32_e32 v20, 1.0, v17
	s_nop 0
	v_addc_co_u32_e32 v17, vcc, 0, v7, vcc
	v_add_co_u32_e32 v18, vcc, 0x2100000, v6
	v_mul_f32_e32 v29, v19, v20
	s_nop 0
	v_addc_co_u32_e32 v19, vcc, 0, v7, vcc
	v_add_co_u32_e32 v20, vcc, 0x3180000, v6
	s_nop 1
	v_addc_co_u32_e32 v21, vcc, 0, v7, vcc
	v_add_co_u32_e32 v22, vcc, 0x4200000, v6
	s_nop 1
	v_addc_co_u32_e32 v23, vcc, 0, v7, vcc
	v_add_co_u32_e32 v24, vcc, 0x5280000, v6
	s_nop 1
	v_addc_co_u32_e32 v25, vcc, 0, v7, vcc
	v_mov_b32_e32 v30, v41
	v_mov_b32_e32 v31, v42
	v_mov_b32_e32 v32, v43
	v_mov_b32_e32 v33, v44
	v_mov_b32_e32 v34, v45
	v_mov_b32_e32 v35, v40
	v_add_co_u32_e32 v26, vcc, 0x6300000, v6
	s_nop 0
	v_mul_f32_e32 v16, v28, v29
	global_store_dword v[10:11], v16, off
	v_mov_b32_e32 v8, v50
	v_addc_co_u32_e32 v27, vcc, 0, v7, vcc
	v_add_co_u32_e32 v6, vcc, 0x7380000, v6
	s_nop 1
	v_addc_co_u32_e32 v7, vcc, 0, v7, vcc
	v_mov_b32_e32 v9, v46
	v_mov_b32_e32 v16, v47
	s_nop 0
	v_add_f32_e32 v6, 0, v35
	v_add_f32_e32 v6, v6, v30
	v_add_f32_e32 v6, v6, v31
	v_add_f32_e32 v6, v6, v32
	v_add_f32_e32 v6, v6, v33
	v_add_f32_e32 v6, v6, v34
	s_nop 0
	v_fmamk_f32 v7, v8, 0x3a800000, v12
	v_mul_f32_e32 v8, 0x4b800000, v7
	v_cmp_gt_f32_e32 vcc, s6, v7
	s_nop 0
	v_add_f32_e32 v6, v6, v9
	v_cndmask_b32_e32 v7, v7, v8, vcc
	v_rsq_f32_e32 v7, v7
	s_nop 0
	v_add_f32_e32 v6, v6, v16
	v_mul_f32_e32 v8, 0x45800000, v7
	v_cndmask_b32_e32 v7, v7, v8, vcc
	v_mul_f32_e32 v7, 0x3c800000, v7
	v_mul_f32_e32 v6, v6, v7
	v_mul_f32_e32 v7, 0x3f3504f3, v6
	v_cmp_nlt_f32_e64 s[4:5], |v7|, 1.0
	s_and_saveexec_b64 s[18:19], s[4:5]
	s_xor_b64 s[4:5], exec, s[18:19]
	s_cbranch_execz .LBB0_987
	v_fma_f32 v8, |v7|, s7, v14
	v_fma_f32 v8, |v7|, v8, s8
	v_fma_f32 v8, |v7|, v8, s9
	v_fma_f32 v8, |v7|, v8, s10
	v_fma_f32 v8, |v7|, v8, s11
	v_fma_f32 v8, |v7|, v8, s12
	v_fma_f32 v8, |v7|, v8, |v7|
	v_mul_f32_e32 v9, 0xbfb8aa3b, v8
	v_fma_f32 v16, v8, s13, -v9
	v_rndne_f32_e32 v17, v9
	v_fmac_f32_e32 v16, 0xb2a5705f, v8
	v_sub_f32_e32 v9, v9, v17
	v_add_f32_e32 v9, v9, v16
	v_cvt_i32_f32_e32 v16, v17
	v_exp_f32_e32 v9, v9
	v_cmp_nlt_f32_e32 vcc, s14, v8
	v_ldexp_f32 v9, v9, v16
	s_nop 0
	v_cndmask_b32_e32 v9, 0, v9, vcc
	v_cmp_ngt_f32_e32 vcc, s15, v8
	s_nop 1
	v_cndmask_b32_e32 v8, v15, v9, vcc
	v_sub_f32_e32 v8, 1.0, v8
